# t12 + P5 PV waves: no V DMA before the first MFMA of a step (all 8 issued behind MFMAs 1,3,..,15)
# baseline (speedup 1.0000x reference)
; #define SBAR() __builtin_amdgcn_sched_barrier(0)
; #define RS_BAR() do { asm volatile("s_waitcnt lgkmcnt(0)" ::: "memory"); __builtin_amdgcn_s_barrier(); asm volatile("" ::: "memory"); } while (0)
; #define VM0() asm volatile("s_waitcnt vmcnt(0)" ::: "memory")
; #define VM0() asm volatile("s_waitcnt vmcnt(0)" ::: "memory")
; #define VMMA(OD, F) do { OD = __builtin_amdgcn_mfma_f32_32x32x16_bf16(pa0, PKF(F[0], F[1]), OD, 0, 0, 0); OD = __builtin_amdgcn_mfma_f32_32x32x16_bf16(pa1, PKF(F[2], F[3]), OD, 0, 0, 0); \
;       OD = __builtin_amdgcn_mfma_f32_32x32x16_bf16(pa2, PKF(F[4], F[5]), OD, 0, 0, 0); OD = __builtin_amdgcn_mfma_f32_32x32x16_bf16(pa3, PKF(F[6], F[7]), OD, 0, 0, 0); } while (0)
; #define LW(n) do { asm volatile("s_waitcnt lgkmcnt(" #n ")" ::: "memory"); SBAR(); } while (0)
; template <class Epi>
; __device__ __forceinline__ void attn_rs_body(const bf16* __restrict__ Qb, const bf16* __restrict__ Kc, const bf16* __restrict__ V0c, const bf16* __restrict__ V1c, int NT, char* lds, const Epi& epi) {
;     ...
;       const int vb = vb0 + b * 32768;
;       s16x4 fa[8], fb[8];
;       { const int tv = j < NT ? j : NT - 1; VDMA(tv, b ^ 1); }
;       asm volatile("s_waitcnt lgkmcnt(0)" ::: "memory"); SBAR();
;       VRD(fa, 0, 0); VRD(fb, 1, 0); LW(8); VMMA(o[0], fa);
;       VRD(fa, 2, 0); LW(8); VMMA(o[1], fb);
;       VRD(fb, 3, 0); LW(8); VMMA(o[2], fa);
;       VRD(fa, 0, 1); LW(8); VMMA(o[3], fb);
;       VRD(fb, 1, 1); LW(8); VMMA(o[4], fa);
;       VRD(fa, 2, 1); LW(8); VMMA(o[5], fb);
;       VRD(fb, 3, 1); LW(8); VMMA(o[6], fa);
;       LW(0); VMMA(o[7], fb);
;       VM0(); RS_BAR();
;     }
.LBB0_500:
	s_lshl_b32 s72, s72, 15
	v_lshl_add_u64 v[244:245], v[176:177], 0, s[48:49]
	s_add_i32 s72, s51, s72
	v_lshl_add_u64 v[246:247], v[174:175], 0, s[48:49]
	v_lshl_add_u32 v0, s71, 15, v182
	s_waitcnt lgkmcnt(0)
	ds_read_b64_tr_b16 v[146:147], v0 offset:0
	ds_read_b64_tr_b16 v[148:149], v0 offset:0x800
	ds_read_b64_tr_b16 v[150:151], v0 offset:0x1000
	ds_read_b64_tr_b16 v[152:153], v0 offset:0x1800
	ds_read_b64_tr_b16 v[154:155], v0 offset:0x2000
	ds_read_b64_tr_b16 v[156:157], v0 offset:0x2800
	ds_read_b64_tr_b16 v[158:159], v0 offset:0x3000
	ds_read_b64_tr_b16 v[160:161], v0 offset:0x3800
	ds_read_b64_tr_b16 v[184:185], v0 offset:0x200
	ds_read_b64_tr_b16 v[186:187], v0 offset:0xa00
	ds_read_b64_tr_b16 v[188:189], v0 offset:0x1200
	ds_read_b64_tr_b16 v[190:191], v0 offset:0x1a00
	ds_read_b64_tr_b16 v[192:193], v0 offset:0x2200
	ds_read_b64_tr_b16 v[194:195], v0 offset:0x2a00
	ds_read_b64_tr_b16 v[196:197], v0 offset:0x3200
	ds_read_b64_tr_b16 v[198:199], v0 offset:0x3a00
	s_waitcnt lgkmcnt(8)
	s_nop 0
	v_mfma_f32_32x32x16_bf16 v[114:129], v[142:145], v[146:149], v[114:129]
	ds_read_b64_tr_b16 v[146:147], v0 offset:0x400
	ds_read_b64_tr_b16 v[148:149], v0 offset:0xc00
	s_add_i32 m0, s72, 0x8000
	v_lshl_add_u64 v[248:249], v[244:245], 0, s[12:13]
	global_load_lds_dwordx4 v[248:249], off
	v_mfma_f32_32x32x16_bf16 v[114:129], v[138:141], v[150:153], v[114:129]
	ds_read_b64_tr_b16 v[150:151], v0 offset:0x1400
	ds_read_b64_tr_b16 v[152:153], v0 offset:0x1c00
	v_mfma_f32_32x32x16_bf16 v[114:129], v[134:137], v[154:157], v[114:129]
	ds_read_b64_tr_b16 v[154:155], v0 offset:0x2400
	ds_read_b64_tr_b16 v[156:157], v0 offset:0x2c00
	s_add_i32 m0, s72, 0xc000
	v_lshl_add_u64 v[250:251], v[244:245], 0, s[14:15]
	global_load_lds_dwordx4 v[250:251], off
	v_mfma_f32_32x32x16_bf16 v[114:129], v[130:133], v[158:161], v[114:129]
	ds_read_b64_tr_b16 v[158:159], v0 offset:0x3400
	ds_read_b64_tr_b16 v[160:161], v0 offset:0x3c00
	s_waitcnt lgkmcnt(8)
	v_mfma_f32_32x32x16_bf16 v[98:113], v[142:145], v[184:187], v[98:113]
	ds_read_b64_tr_b16 v[184:185], v0 offset:0x600
	ds_read_b64_tr_b16 v[186:187], v0 offset:0xe00
	s_add_i32 m0, s72, 0x8400
	v_lshl_add_u64 v[248:249], v[244:245], 0, s[16:17]
	global_load_lds_dwordx4 v[248:249], off
	v_mfma_f32_32x32x16_bf16 v[98:113], v[138:141], v[188:191], v[98:113]
	ds_read_b64_tr_b16 v[188:189], v0 offset:0x1600
	ds_read_b64_tr_b16 v[190:191], v0 offset:0x1e00
	v_mfma_f32_32x32x16_bf16 v[98:113], v[134:137], v[192:195], v[98:113]
	ds_read_b64_tr_b16 v[192:193], v0 offset:0x2600
	ds_read_b64_tr_b16 v[194:195], v0 offset:0x2e00
	s_add_i32 m0, s72, 0xc400
	v_lshl_add_u64 v[250:251], v[244:245], 0, s[18:19]
	global_load_lds_dwordx4 v[250:251], off
	v_mfma_f32_32x32x16_bf16 v[98:113], v[130:133], v[196:199], v[98:113]
	ds_read_b64_tr_b16 v[196:197], v0 offset:0x3600
	ds_read_b64_tr_b16 v[198:199], v0 offset:0x3e00
	s_waitcnt lgkmcnt(8)
	v_mfma_f32_32x32x16_bf16 v[82:97], v[142:145], v[146:149], v[82:97]
	ds_read_b64_tr_b16 v[146:147], v0 offset:0x4000
	ds_read_b64_tr_b16 v[148:149], v0 offset:0x4800
	s_add_i32 m0, s72, 0x8800
	v_lshl_add_u64 v[248:249], v[246:247], 0, s[12:13]
	global_load_lds_dwordx4 v[248:249], off
	v_mfma_f32_32x32x16_bf16 v[82:97], v[138:141], v[150:153], v[82:97]
	ds_read_b64_tr_b16 v[150:151], v0 offset:0x5000
	ds_read_b64_tr_b16 v[152:153], v0 offset:0x5800
	v_mfma_f32_32x32x16_bf16 v[82:97], v[134:137], v[154:157], v[82:97]
	ds_read_b64_tr_b16 v[154:155], v0 offset:0x6000
	ds_read_b64_tr_b16 v[156:157], v0 offset:0x6800
	s_add_i32 m0, s72, 0xc800
	v_lshl_add_u64 v[250:251], v[246:247], 0, s[14:15]
	global_load_lds_dwordx4 v[250:251], off
	v_mfma_f32_32x32x16_bf16 v[82:97], v[130:133], v[158:161], v[82:97]
	ds_read_b64_tr_b16 v[158:159], v0 offset:0x7000
	ds_read_b64_tr_b16 v[160:161], v0 offset:0x7800
	s_waitcnt lgkmcnt(8)
	v_mfma_f32_32x32x16_bf16 v[66:81], v[142:145], v[184:187], v[66:81]
	ds_read_b64_tr_b16 v[184:185], v0 offset:0x4200
	ds_read_b64_tr_b16 v[186:187], v0 offset:0x4a00
	s_add_i32 m0, s72, 0x8c00
	v_lshl_add_u64 v[248:249], v[246:247], 0, s[16:17]
	global_load_lds_dwordx4 v[248:249], off
	v_mfma_f32_32x32x16_bf16 v[66:81], v[138:141], v[188:191], v[66:81]
	ds_read_b64_tr_b16 v[188:189], v0 offset:0x5200
	ds_read_b64_tr_b16 v[190:191], v0 offset:0x5a00
	v_mfma_f32_32x32x16_bf16 v[66:81], v[134:137], v[192:195], v[66:81]
	ds_read_b64_tr_b16 v[192:193], v0 offset:0x6200
	ds_read_b64_tr_b16 v[194:195], v0 offset:0x6a00
	s_add_i32 m0, s72, 0xcc00
	v_lshl_add_u64 v[250:251], v[246:247], 0, s[18:19]
	global_load_lds_dwordx4 v[250:251], off
	v_mfma_f32_32x32x16_bf16 v[66:81], v[130:133], v[196:199], v[66:81]
	ds_read_b64_tr_b16 v[196:197], v0 offset:0x7200
	ds_read_b64_tr_b16 v[198:199], v0 offset:0x7a00
	s_waitcnt lgkmcnt(8)
	v_mfma_f32_32x32x16_bf16 v[50:65], v[142:145], v[146:149], v[50:65]
	ds_read_b64_tr_b16 v[146:147], v0 offset:0x4400
	ds_read_b64_tr_b16 v[148:149], v0 offset:0x4c00
	v_mfma_f32_32x32x16_bf16 v[50:65], v[138:141], v[150:153], v[50:65]
	ds_read_b64_tr_b16 v[150:151], v0 offset:0x5400
	ds_read_b64_tr_b16 v[152:153], v0 offset:0x5c00
	v_mfma_f32_32x32x16_bf16 v[50:65], v[134:137], v[154:157], v[50:65]
	ds_read_b64_tr_b16 v[154:155], v0 offset:0x6400
	ds_read_b64_tr_b16 v[156:157], v0 offset:0x6c00
	v_mfma_f32_32x32x16_bf16 v[50:65], v[130:133], v[158:161], v[50:65]
	ds_read_b64_tr_b16 v[158:159], v0 offset:0x7400
	ds_read_b64_tr_b16 v[160:161], v0 offset:0x7c00
	s_waitcnt lgkmcnt(8)
	v_mfma_f32_32x32x16_bf16 v[34:49], v[142:145], v[184:187], v[34:49]
	ds_read_b64_tr_b16 v[184:185], v0 offset:0x4600
	ds_read_b64_tr_b16 v[186:187], v0 offset:0x4e00
	v_mfma_f32_32x32x16_bf16 v[34:49], v[138:141], v[188:191], v[34:49]
	ds_read_b64_tr_b16 v[188:189], v0 offset:0x5600
	ds_read_b64_tr_b16 v[190:191], v0 offset:0x5e00
	v_mfma_f32_32x32x16_bf16 v[34:49], v[134:137], v[192:195], v[34:49]
	ds_read_b64_tr_b16 v[192:193], v0 offset:0x6600
	ds_read_b64_tr_b16 v[194:195], v0 offset:0x6e00
	v_mfma_f32_32x32x16_bf16 v[34:49], v[130:133], v[196:199], v[34:49]
	ds_read_b64_tr_b16 v[196:197], v0 offset:0x7600
	ds_read_b64_tr_b16 v[198:199], v0 offset:0x7e00
	s_waitcnt lgkmcnt(8)
	s_waitcnt lgkmcnt(0)
	s_waitcnt vmcnt(0)
	s_add_i32 s70, s70, 1
	s_waitcnt lgkmcnt(0)
	s_barrier
	s_add_u32 s48, s48, 0x4000
	s_addc_u32 s49, s49, 0
	v_mfma_f32_32x32x16_bf16 v[18:33], v[142:145], v[146:149], v[18:33]
	v_mfma_f32_32x32x16_bf16 v[2:17], v[142:145], v[184:187], v[2:17]
	v_mfma_f32_32x32x16_bf16 v[18:33], v[138:141], v[150:153], v[18:33]
	v_mfma_f32_32x32x16_bf16 v[2:17], v[138:141], v[188:191], v[2:17]
	v_mfma_f32_32x32x16_bf16 v[18:33], v[134:137], v[154:157], v[18:33]
	v_mfma_f32_32x32x16_bf16 v[2:17], v[134:137], v[192:195], v[2:17]
	s_cmp_eq_u32 s48, 0x1fc000
	v_mfma_f32_32x32x16_bf16 v[18:33], v[130:133], v[158:161], v[18:33]
	v_mfma_f32_32x32x16_bf16 v[2:17], v[130:133], v[196:199], v[2:17]
	s_cbranch_scc1 .LBB0_503
